# oddprep row pass: the row's ckv / fq / fk loads issued at the top of the trip with the cq loads instead of one at a time behind vmcnt(0) in the dependent chain
# speedup vs baseline: 1.0182x; 1.0123x over previous
; DEVI float bf_lo(unsigned u) { return __uint_as_float(u << 16); }
; __device__ __forceinline__ void oddprep_phase(const Params& p) {
;     ...
;     {
;       unsigned u[3]; float ss = 0.f;
; #pragma unroll
;       for (int j = 0; j < 3; ++j) { u[j] = *(const unsigned*)(zr + 128 * j + 2 * lane); ss += bf_lo(u[j]) * bf_lo(u[j]) + bf_hi(u[j]) * bf_hi(u[j]); }
;       ss = wave_sum(ss); const float rs = rsqrtf(ss * (1.0f / 384.0f) + EPS);
; #pragma unroll
;       for (int j = 0; j < 3; ++j) { const float* gp = p.od_g_qa + 128 * j + 2 * lane; *(unsigned*)(zr + 128 * j + 2 * lane) = pk_bf16(bf_lo(u[j]) * rs * gp[0], bf_hi(u[j]) * rs * gp[1]); }
;     }
;     {
;       const uint2 u = *(const uint2*)(zr + 384 + 4 * lane);
;       float v0 = bf_lo(u.x), v1 = bf_hi(u.x), v2 = bf_lo(u.y), v3 = bf_hi(u.y);
;       float ss = wave_sum(v0 * v0 + v1 * v1 + v2 * v2 + v3 * v3); const float rs = rsqrtf(ss * (1.0f / 256.0f) + EPS);
;       const float* gp = p.od_g_kva + 4 * lane; uint2 o; o.x = pk_bf16(v0 * rs * gp[0], v1 * rs * gp[1]); o.y = pk_bf16(v2 * rs * gp[2], v3 * rs * gp[3]);
;       *(uint2*)(zr + 384 + 4 * lane) = o;
;     }
;     {
;       const int b = r / T, t = r - b * T;
;       const int pos = t < 16 ? t : p.pos[b * 4096 + (t - 16)] + 16;
;       const int i = lane & 15;
;       const float freq = exp2f(-(float)i * 0.8304820237218406f);
;       const float ang = (float)pos * freq;
;       double rev = (double)ang * 0.15915494309189535; rev -= rint(rev);
;       const float rf = (float)rev;
;       const float cs = __builtin_amdgcn_cosf(rf), sn = __builtin_amdgcn_sinf(rf);
;       float v = lane < 32 ? bf2f(zr[640 + lane]) : 0.f;
;       const float ss = wave_sum(v * v); const float rs = rsqrtf(ss * (1.0f / 32.0f) + EPS);
;       const float kn = lane < 32 ? v * rs * p.od_g_kr[lane & 31] : 0.f;
;       const float pt = __shfl_xor(kn, 16);
;       const float o = lane < 16 ? kn * cs - pt * sn : pt * sn + kn * cs;
;       if (lane < 32) KR[(size_t)r * 32 + lane] = f2bf(o);
;       if (lane < 16) { ROPE[(size_t)r * 32 + lane] = cs; ROPE[(size_t)r * 32 + 16 + lane] = sn; }
;     }
; #pragma unroll
;     for (int which = 0; which < 2; ++which) {
;       bf16_t* base = zr + (which ? 1184 : 672) + 8 * lane; const float* gg = (which ? p.od_g_fk : p.od_g_fq) + 8 * (lane & 7);
;       const uint4 u = *(const uint4*)base; const unsigned uu[4] = {u.x, u.y, u.z, u.w};
.LBB0_1263:
	v_readlane_b32 s16, v253, 2
	v_readlane_b32 s18, v253, 4
	v_readlane_b32 s19, v253, 5
	s_mov_b32 s10, 0x7895000
	v_readlane_b32 s17, v253, 3
	v_lshl_add_u64 v[0:1], s[18:19], 0, v[26:27]
	v_add_co_u32_e32 v0, vcc, 0x7895000, v0
	s_nop 1
	v_addc_co_u32_e32 v1, vcc, 0, v1, vcc
	global_load_dword v5, v[0:1], off offset:2304
	global_load_dword v3, v[0:1], off offset:2560
	global_load_dword v36, v[0:1], off offset:2816
	v_lshl_add_u64 v[92:93], s[18:19], 0, v[30:31]
	v_add_co_u32_e32 v92, vcc, 0x7895000, v92
	s_nop 1
	v_addc_co_u32_e32 v93, vcc, 0, v93, vcc
	global_load_dwordx4 v[96:99], v[92:93], off offset:3648
	v_add_co_u32_e32 v94, vcc, 0x1000, v92
	s_nop 1
	v_addc_co_u32_e32 v95, vcc, 0, v93, vcc
	global_load_dwordx4 v[100:103], v[94:95], off offset:576
	v_lshl_add_u64 v[94:95], s[18:19], 0, v[24:25]
	v_add_co_u32_e32 v94, vcc, 0x7895000, v94
	s_nop 1
	v_addc_co_u32_e32 v95, vcc, 0, v95, vcc
	global_load_dwordx2 v[104:105], v[94:95], off offset:3072
	s_waitcnt vmcnt(5)
	v_lshlrev_b32_e32 v34, 16, v5
	s_waitcnt vmcnt(4)
	v_lshlrev_b32_e32 v2, 16, v3
	v_and_b32_e32 v3, 0xffff0000, v3
	s_waitcnt vmcnt(3)
	v_lshlrev_b32_e32 v35, 16, v36
	v_and_b32_e32 v37, 0xffff0000, v36
	v_and_b32_e32 v36, 0xffff0000, v5
	v_pk_mul_f32 v[32:33], v[2:3], v[2:3]
	v_pk_mul_f32 v[46:47], v[36:37], v[36:37]
	v_add_f32_e32 v5, v32, v33
	v_pk_fma_f32 v[46:47], v[34:35], v[34:35], v[46:47]
	s_nop 0
	v_add_f32_e32 v5, v46, v5
	v_add_f32_e32 v5, v5, v47
	ds_bpermute_b32 v32, v38, v5
	s_waitcnt lgkmcnt(0)
	v_add_f32_e32 v5, v5, v32
	ds_bpermute_b32 v32, v39, v5
	s_waitcnt lgkmcnt(0)
	v_add_f32_e32 v5, v5, v32
	ds_bpermute_b32 v32, v40, v5
	s_waitcnt lgkmcnt(0)
	v_add_f32_e32 v5, v5, v32
	ds_bpermute_b32 v32, v41, v5
	s_waitcnt lgkmcnt(0)
	v_add_f32_e32 v5, v5, v32
	ds_bpermute_b32 v32, v42, v5
	s_waitcnt lgkmcnt(0)
	v_add_f32_e32 v5, v5, v32
	ds_bpermute_b32 v32, v43, v5
	s_waitcnt lgkmcnt(0)
	v_add_f32_e32 v5, v5, v32
	v_fmamk_f32 v5, v5, 0x3b2aaaab, v132
	v_cmp_gt_f32_e32 vcc, s81, v5
	v_mul_f32_e32 v32, 0x4b800000, v5
	s_nop 0
	v_cndmask_b32_e32 v5, v5, v32, vcc
	v_rsq_f32_e32 v5, v5
	s_nop 0
	v_mul_f32_e32 v32, 0x45800000, v5
	v_cndmask_b32_e32 v5, v5, v32, vcc
	v_mul_f32_e32 v34, v5, v34
	v_mul_f32_e32 v2, v5, v2
	v_mul_f32_e32 v3, v5, v3
	s_nop 1
	v_mov_b64_e32 v[32:33], v[64:65]
	v_mul_f32_e32 v32, v32, v34
	v_mul_f32_e32 v34, v5, v36
	v_mul_f32_e32 v33, v33, v34
	v_cvt_pk_bf16_f32 v32, v32, v33
	global_store_dword v[0:1], v32, off offset:2304
	s_nop 1
	v_mov_b64_e32 v[32:33], v[66:67]
	v_mul_f32_e32 v2, v32, v2
	v_mul_f32_e32 v3, v33, v3
	v_cvt_pk_bf16_f32 v2, v2, v3
	global_store_dword v[0:1], v2, off offset:2560
	v_mul_f32_e32 v32, v5, v35
	v_mul_f32_e32 v5, v5, v37
	s_nop 1
	v_mov_b64_e32 v[2:3], v[68:69]
	v_mul_f32_e32 v2, v2, v32
	v_mul_f32_e32 v3, v3, v5
	v_cvt_pk_bf16_f32 v2, v2, v3
	global_store_dword v[0:1], v2, off offset:2816
	v_lshl_add_u64 v[0:1], s[18:19], 0, v[24:25]
	v_add_co_u32_e32 v32, vcc, s10, v0
	s_nop 1
	v_addc_co_u32_e32 v33, vcc, 0, v1, vcc
	s_waitcnt vmcnt(0)
	v_mov_b64_e32 v[0:1], v[104:105]
	v_lshlrev_b32_e32 v34, 16, v0
	v_and_b32_e32 v35, 0xffff0000, v0
	v_lshlrev_b32_e32 v37, 16, v1
	v_and_b32_e32 v36, 0xffff0000, v1
	v_pk_mul_f32 v[0:1], v[34:35], v[34:35]
	v_pk_mul_f32 v[2:3], v[36:37], v[36:37]
	v_add_f32_e32 v0, v0, v1
	v_add_f32_e32 v0, v0, v3
	v_add_f32_e32 v0, v2, v0
	ds_bpermute_b32 v1, v38, v0
	s_waitcnt lgkmcnt(0)
	v_add_f32_e32 v0, v0, v1
	ds_bpermute_b32 v1, v39, v0
	s_waitcnt lgkmcnt(0)
	v_add_f32_e32 v0, v0, v1
	ds_bpermute_b32 v1, v40, v0
	s_waitcnt lgkmcnt(0)
	v_add_f32_e32 v0, v0, v1
	ds_bpermute_b32 v1, v41, v0
	s_waitcnt lgkmcnt(0)
	v_add_f32_e32 v0, v0, v1
	ds_bpermute_b32 v1, v42, v0
	s_waitcnt lgkmcnt(0)
	v_add_f32_e32 v0, v0, v1
	ds_bpermute_b32 v1, v43, v0
	s_waitcnt lgkmcnt(0)
	v_add_f32_e32 v0, v0, v1
	v_fmamk_f32 v0, v0, 0x3b800000, v132
	v_cmp_gt_f32_e32 vcc, s81, v0
	v_mul_f32_e32 v1, 0x4b800000, v0
	s_nop 0
	v_cndmask_b32_e32 v0, v0, v1, vcc
	v_rsq_f32_e32 v0, v0
	s_nop 0
	v_mul_f32_e32 v1, 0x45800000, v0
	v_cndmask_b32_e32 v5, v0, v1, vcc
	v_mul_f32_e32 v34, v5, v34
	s_nop 1
	v_mov_b64_e32 v[0:1], v[72:73]
	v_mov_b64_e32 v[2:3], v[74:75]
	v_mul_f32_e32 v0, v0, v34
	v_mul_f32_e32 v34, v5, v35
	v_mul_f32_e32 v1, v1, v34
	v_cvt_pk_bf16_f32 v0, v0, v1
	v_mul_f32_e32 v1, v5, v37
	v_mul_f32_e32 v1, v2, v1
	v_mul_f32_e32 v2, v5, v36
	v_mul_f32_e32 v2, v3, v2
	v_cvt_pk_bf16_f32 v1, v1, v2
	global_store_dwordx2 v[32:33], v[0:1], off offset:3072
	v_mul_hi_i32 v0, v4, s23
	v_lshrrev_b32_e32 v1, 31, v0
	v_ashrrev_i32_e32 v0, 11, v0
	v_add_u32_e32 v1, v0, v1
	v_mad_i32_i24 v0, v1, s24, v4
	v_cmp_lt_i32_e32 vcc, 15, v0
	s_and_saveexec_b64 s[10:11], vcc
	s_cbranch_execz .LBB0_1265
	v_mul_i32_i24_e32 v0, 0xffffeff0, v1
	v_lshl_add_u32 v0, v1, 12, v0
	v_add3_u32 v0, v4, v0, -16
	v_readlane_b32 s36, v253, 28
	v_ashrrev_i32_e32 v1, 31, v0
	v_readlane_b32 s38, v253, 30
	v_readlane_b32 s39, v253, 31
	v_readlane_b32 s37, v253, 29
	v_readlane_b32 s40, v253, 32
	v_lshl_add_u64 v[0:1], v[0:1], 2, s[38:39]
	global_load_dword v0, v[0:1], off
	v_readlane_b32 s41, v253, 33
	v_readlane_b32 s42, v253, 34
	v_readlane_b32 s43, v253, 35
	v_readlane_b32 s44, v253, 36
	v_readlane_b32 s45, v253, 37
	v_readlane_b32 s46, v253, 38
	v_readlane_b32 s47, v253, 39
	v_readlane_b32 s48, v253, 40
	v_readlane_b32 s49, v253, 41
	v_readlane_b32 s50, v253, 42
	v_readlane_b32 s51, v253, 43
	s_waitcnt vmcnt(0)
	v_add_u32_e32 v0, 16, v0

; DEVI unsigned pk_bf16(float lo, float hi) { unsigned r; asm("v_cvt_pk_bf16_f32 %0, %1, %2" : "=v"(r) : "v"(lo), "v"(hi)); return r; }
; DEVI float bf_lo(unsigned u) { return __uint_as_float(u << 16); }
; DEVI float bf_hi(unsigned u) { return __uint_as_float(u & 0xffff0000u); }
; DEVI float logsigmoidf_(float x) { return fminf(x, 0.f) - 0.6931471805599453f * __builtin_amdgcn_logf(1.0f + __builtin_amdgcn_exp2f(-fabsf(x) * LOG2E)); }
; __device__ __forceinline__ void oddprep_phase(const Params& p) {
;     ...
; #pragma unroll
;     for (int which = 0; which < 2; ++which) {
;       bf16_t* base = zr + (which ? 1184 : 672) + 8 * lane; const float* gg = (which ? p.od_g_fk : p.od_g_fq) + 8 * (lane & 7);
;       const uint4 u = *(const uint4*)base; const unsigned uu[4] = {u.x, u.y, u.z, u.w};
;       float v[8]; float ss = 0.f;
; #pragma unroll
;       for (int j = 0; j < 4; ++j) { v[2 * j] = bf_lo(uu[j]); v[2 * j + 1] = bf_hi(uu[j]); ss += v[2 * j] * v[2 * j] + v[2 * j + 1] * v[2 * j + 1]; }
;       ss += __shfl_xor(ss, 1); ss += __shfl_xor(ss, 2); ss += __shfl_xor(ss, 4);
;       const float rs = rsqrtf(ss * (1.0f / 64.0f) + EPS);
;       *(uint4*)base = make_uint4(pk_bf16(v[0] * rs * gg[0], v[1] * rs * gg[1]), pk_bf16(v[2] * rs * gg[2], v[3] * rs * gg[3]), pk_bf16(v[4] * rs * gg[4], v[5] * rs * gg[5]), pk_bf16(v[6] * rs * gg[6], v[7] * rs * gg[7]));
;     }
;     if (lane < 8) { float* gp = G + (size_t)r * 8 + lane; *gp = logsigmoidf_(*gp + p.od_b_f[lane]); }
.LBB0_1273:
	s_or_b64 exec, exec, s[10:11]
	v_readlane_b32 s16, v253, 2
	v_readlane_b32 s18, v253, 4
	v_readlane_b32 s19, v253, 5
	s_mov_b32 s10, 0x7896000
	v_readlane_b32 s17, v253, 3
	v_lshl_add_u64 v[0:1], s[18:19], 0, v[30:31]
	v_add_co_u32_e32 v2, vcc, 0x7895000, v0
	s_waitcnt lgkmcnt(0)
	s_nop 0
	v_addc_co_u32_e32 v3, vcc, 0, v1, vcc
	s_waitcnt vmcnt(0)
	v_mov_b64_e32 v[32:33], v[96:97]
	v_mov_b64_e32 v[34:35], v[98:99]
	v_and_b32_e32 v47, 0xffff0000, v33
	v_and_b32_e32 v46, 0xffff0000, v32
	v_lshlrev_b32_e32 v37, 16, v33
	v_lshlrev_b32_e32 v36, 16, v32
	v_pk_mul_f32 v[32:33], v[46:47], v[46:47]
	v_and_b32_e32 v51, 0xffff0000, v35
	v_and_b32_e32 v50, 0xffff0000, v34
	v_pk_fma_f32 v[32:33], v[36:37], v[36:37], v[32:33]
	v_lshlrev_b32_e32 v49, 16, v35
	v_lshlrev_b32_e32 v48, 16, v34
	v_pk_mul_f32 v[34:35], v[50:51], v[50:51]
	v_add_f32_e32 v5, v32, v33
	v_pk_fma_f32 v[34:35], v[48:49], v[48:49], v[34:35]
	s_nop 0
	v_add_f32_e32 v5, v5, v34
	v_add_f32_e32 v5, v5, v35
	ds_bpermute_b32 v32, v43, v5
	s_waitcnt lgkmcnt(0)
	v_add_f32_e32 v5, v5, v32
	ds_bpermute_b32 v32, v42, v5
	s_waitcnt lgkmcnt(0)
	v_add_f32_e32 v5, v5, v32
	ds_bpermute_b32 v32, v41, v5
	s_waitcnt lgkmcnt(0)
	v_add_f32_e32 v5, v5, v32
	v_fmamk_f32 v5, v5, 0x3c800000, v132
	v_cmp_gt_f32_e32 vcc, s81, v5
	v_mul_f32_e32 v32, 0x4b800000, v5
	s_nop 0
	v_cndmask_b32_e32 v5, v5, v32, vcc
	v_rsq_f32_e32 v5, v5
	s_nop 0
	v_mul_f32_e32 v32, 0x45800000, v5
	v_cndmask_b32_e32 v5, v5, v32, vcc
	v_mul_f32_e32 v36, v5, v36
	v_mul_f32_e32 v45, v5, v48
	s_nop 1
	v_mov_b64_e32 v[32:33], v[76:77]
	v_mov_b64_e32 v[34:35], v[78:79]
	v_mul_f32_e32 v32, v32, v36
	v_mul_f32_e32 v36, v5, v46
	v_mul_f32_e32 v33, v33, v36
	v_cvt_pk_bf16_f32 v32, v32, v33
	v_mul_f32_e32 v33, v5, v37
	v_mul_f32_e32 v33, v34, v33
	v_mul_f32_e32 v34, v5, v47
	v_mul_f32_e32 v34, v35, v34
	v_cvt_pk_bf16_f32 v33, v33, v34
	s_nop 1
	v_mov_b64_e32 v[34:35], v[80:81]
	v_mov_b64_e32 v[36:37], v[82:83]
	v_mul_f32_e32 v34, v34, v45
	v_mul_f32_e32 v45, v5, v50
	v_mul_f32_e32 v35, v35, v45
	v_cvt_pk_bf16_f32 v34, v34, v35
	v_mul_f32_e32 v35, v5, v49
	v_mul_f32_e32 v35, v36, v35
	v_mul_f32_e32 v5, v5, v51
	v_mul_f32_e32 v5, v37, v5
	v_cvt_pk_bf16_f32 v35, v35, v5
	global_store_dwordx4 v[2:3], v[32:35], off offset:3648
	s_nop 1
	v_add_co_u32_e32 v32, vcc, s10, v0
	s_nop 1
	v_addc_co_u32_e32 v33, vcc, 0, v1, vcc
	s_waitcnt vmcnt(0)
	v_mov_b64_e32 v[0:1], v[100:101]
	v_mov_b64_e32 v[2:3], v[102:103]
	v_lshlrev_b32_e32 v37, 16, v1
	v_lshlrev_b32_e32 v36, 16, v0
	v_and_b32_e32 v1, 0xffff0000, v1
	v_and_b32_e32 v0, 0xffff0000, v0
	v_pk_mul_f32 v[34:35], v[0:1], v[0:1]
	s_nop 0
	v_pk_fma_f32 v[46:47], v[36:37], v[36:37], v[34:35]
	v_lshlrev_b32_e32 v35, 16, v3
	v_lshlrev_b32_e32 v34, 16, v2
	v_and_b32_e32 v3, 0xffff0000, v3
	v_and_b32_e32 v2, 0xffff0000, v2
	v_pk_mul_f32 v[48:49], v[2:3], v[2:3]
	v_add_f32_e32 v5, v46, v47
	v_pk_fma_f32 v[48:49], v[34:35], v[34:35], v[48:49]
	s_nop 0
	v_add_f32_e32 v5, v5, v48
	v_add_f32_e32 v5, v5, v49
	ds_bpermute_b32 v45, v43, v5
	s_waitcnt lgkmcnt(0)
	v_add_f32_e32 v5, v5, v45
	ds_bpermute_b32 v45, v42, v5
	s_waitcnt lgkmcnt(0)
	v_add_f32_e32 v5, v5, v45
	ds_bpermute_b32 v45, v41, v5
	s_waitcnt lgkmcnt(0)
	v_add_f32_e32 v5, v5, v45
	v_fmamk_f32 v5, v5, 0x3c800000, v132
	v_cmp_gt_f32_e32 vcc, s81, v5
	v_mul_f32_e32 v45, 0x4b800000, v5
	s_nop 0
	v_cndmask_b32_e32 v5, v5, v45, vcc
	v_rsq_f32_e32 v5, v5
	s_nop 0
	v_mul_f32_e32 v45, 0x45800000, v5
	v_cndmask_b32_e32 v5, v5, v45, vcc
	v_mul_f32_e32 v36, v5, v36
	v_mul_f32_e32 v0, v5, v0
	v_mul_f32_e32 v1, v5, v1
	v_mul_f32_e32 v34, v5, v34
	v_mul_f32_e32 v2, v5, v2
	v_mul_f32_e32 v3, v5, v3
	s_nop 1
	v_mov_b64_e32 v[46:47], v[84:85]
	v_mov_b64_e32 v[48:49], v[86:87]
	v_mul_f32_e32 v36, v46, v36
	v_mul_f32_e32 v0, v47, v0
	v_cvt_pk_bf16_f32 v0, v36, v0
	v_mul_f32_e32 v36, v5, v37
	v_mul_f32_e32 v36, v48, v36
	v_mul_f32_e32 v1, v49, v1
	v_cvt_pk_bf16_f32 v1, v36, v1
	s_nop 1
	v_mov_b64_e32 v[46:47], v[88:89]
	v_mov_b64_e32 v[48:49], v[90:91]
	v_mul_f32_e32 v34, v46, v34
	v_mul_f32_e32 v2, v47, v2
	v_cvt_pk_bf16_f32 v2, v34, v2
	v_mul_f32_e32 v34, v5, v35
	v_mul_f32_e32 v3, v49, v3
	v_mul_f32_e32 v34, v48, v34
	v_cvt_pk_bf16_f32 v3, v34, v3
	global_store_dwordx4 v[32:33], v[0:3], off offset:576
	s_and_saveexec_b64 s[10:11], s[6:7]
	s_cbranch_execz .LBB0_1262
	v_readlane_b32 s16, v253, 2
	v_readlane_b32 s18, v253, 4
	v_readlane_b32 s19, v253, 5
	s_mov_b32 s16, 0xbfb8aa3b
	v_readlane_b32 s17, v253, 3
	v_lshl_add_u64 v[0:1], s[18:19], 0, v[22:23]
	global_load_dword v2, v[0:1], off
	global_load_dword v3, v[16:17], off
	s_waitcnt vmcnt(0)
	v_add_f32_e32 v2, v2, v3
	v_mul_f32_e64 v3, |v2|, s16
	v_exp_f32_e32 v3, v3
	v_min_f32_e32 v2, 0, v2
	v_add_f32_e32 v3, 1.0, v3
	v_log_f32_e32 v3, v3
	s_nop 0
	v_fmac_f32_e32 v2, 0xbf317218, v3
	global_store_dword v[0:1], v2, off
	s_branch .LBB0_1262
